# DPP / permlane16_swap instead of LDS bpermute round trips for the 80 RMS-norm butterfly steps of the attention epilogue (instruction selection lever)
# speedup vs baseline: 1.0157x; 1.0136x over previous
; __device__ __forceinline__ unsigned f2bf(float f) { unsigned u = __builtin_bit_cast(unsigned, f); return (u + 0x7fffu + ((u >> 16) & 1u)) >> 16; }
; __device__ __forceinline__ int crow(int r, int hi) { return (r & 3) + 8 * (r >> 2) + 4 * hi; }
; __device__ __forceinline__ void attn_unit(const bf16* __restrict__ Qb, const bf16* __restrict__ Kh, const bf16* __restrict__ Vh, int klat0, int nlt, int kctx0, int NT,
;                                           float lam, float post, const float* __restrict__ subw, bf16* __restrict__ Ob, char* lds) {
;     ...
;   __syncthreads();
;   if (sbr == 0) {
;     float sw[4];
; #pragma unroll
;     for (int d0 = 0; d0 < 4; ++d0) sw[d0] = subw[d0 * 32 + r32_e] * post;
;     bf16* Ow = Ob + (long)(wq_e * 32) * DM;
; #pragma unroll
;     for (int r = 0; r < 16; ++r) { const int orow = crow(r, hi_e); float v[4]; float ss = 0.f;
; #pragma unroll
;       for (int d0 = 0; d0 < 4; ++d0) { v[d0] = o[d0][r] - lam * X[(wq_e * 32 + orow) * 128 + d0 * 32 + r32_e]; ss += v[d0] * v[d0]; }
;       ss += __shfl_xor(ss, 1); ss += __shfl_xor(ss, 2); ss += __shfl_xor(ss, 4); ss += __shfl_xor(ss, 8); ss += __shfl_xor(ss, 16);
;       const float rs = 1.0f / sqrtf(ss * (1.0f / 128.0f) + LN_EPS);
; #pragma unroll
;       for (int d0 = 0; d0 < 4; ++d0) Ow[(long)orow * DM + d0 * 32 + r32_e] = (bf16)f2bf(v[d0] * rs * sw[d0]); }
.LBB0_795:
	s_andn2_b64 vcc, exec, s[6:7]
	s_waitcnt lgkmcnt(0)
	s_barrier
	s_cbranch_vccnz .LBB0_714
	v_lshlrev_b32_e32 v30, 2, v139
	v_ashrrev_i32_e32 v139, 31, v138
	v_lshl_add_u64 v[4:5], v[138:139], 2, s[2:3]
	global_load_dword v8, v[4:5], off
	s_lshl_b64 s[0:1], s[4:5], 12
	v_readlane_b32 s4, v251, 21
	s_add_u32 s0, s4, s0
	v_readlane_b32 s4, v251, 22
	s_addc_u32 s1, s4, s1
	s_mov_b32 s4, 0xf800000
	s_add_u32 s0, s0, s16
	s_addc_u32 s1, s1, 0
	v_ashrrev_i32_e32 v31, 31, v30
	v_add_u32_e32 v28, 8, v30
	v_add_u32_e32 v26, 9, v30
	v_add_u32_e32 v24, 10, v30
	v_add_u32_e32 v22, 11, v30
	v_add_u32_e32 v20, 16, v30
	v_add_u32_e32 v18, 17, v30
	v_add_u32_e32 v16, 18, v30
	v_add_u32_e32 v14, 19, v30
	v_add_u32_e32 v12, 24, v30
	v_add_u32_e32 v10, 25, v30
	v_add_u32_e32 v6, 26, v30
	v_add_u32_e32 v2, 27, v30
	v_ashrrev_i32_e32 v29, 31, v28
	v_ashrrev_i32_e32 v27, 31, v26
	v_ashrrev_i32_e32 v25, 31, v24
	v_ashrrev_i32_e32 v23, 31, v22
	v_ashrrev_i32_e32 v21, 31, v20
	v_ashrrev_i32_e32 v19, 31, v18
	v_ashrrev_i32_e32 v17, 31, v16
	v_ashrrev_i32_e32 v15, 31, v14
	v_ashrrev_i32_e32 v13, 31, v12
	v_ashrrev_i32_e32 v11, 31, v10
	v_ashrrev_i32_e32 v7, 31, v6
	v_ashrrev_i32_e32 v3, 31, v2
	s_waitcnt vmcnt(0)
	v_mul_f32_e32 v34, v161, v8
	global_load_dword v8, v[4:5], off offset:128
	s_waitcnt vmcnt(0)
	v_mul_f32_e32 v35, v161, v8
	global_load_dword v8, v[4:5], off offset:256
	s_waitcnt vmcnt(0)
	v_mul_f32_e32 v36, v161, v8
	global_load_dword v4, v[4:5], off offset:384
	v_lshlrev_b32_e32 v8, 5, v88
	v_ashrrev_i32_e32 v9, 31, v8
	s_waitcnt vmcnt(0)
	v_mul_f32_e32 v37, v161, v4
	v_lshlrev_b64 v[4:5], 12, v[8:9]
	v_add_u32_e32 v9, v30, v8
	v_lshl_add_u32 v9, v9, 7, v138
	v_lshl_add_u32 v9, v9, 2, 0
	ds_read2_b32 v[98:99], v9 offset1:32
	v_lshl_add_u64 v[4:5], s[0:1], 0, v[4:5]
	v_lshl_add_u64 v[4:5], v[138:139], 1, v[4:5]
	s_waitcnt lgkmcnt(0)
	v_fma_f32 v88, -v160, v98, v108
	v_fma_f32 v97, -v160, v99, v109
	ds_read2_b32 v[98:99], v9 offset0:64 offset1:96
	v_mul_f32_e32 v100, v97, v97
	v_fmac_f32_e32 v100, v88, v88
	s_waitcnt lgkmcnt(0)
	v_fma_f32 v9, -v160, v98, v106
	v_fmac_f32_e32 v100, v9, v9
	v_fma_f32 v101, -v160, v99, v107
	v_fmac_f32_e32 v100, v101, v101
	s_nop 1
	v_mov_b32_dpp v98, v100 quad_perm:[1,0,3,2] row_mask:0xf bank_mask:0xf
	s_waitcnt lgkmcnt(0)
	v_add_f32_e32 v98, v100, v98
	s_nop 1
	v_mov_b32_dpp v99, v98 quad_perm:[2,3,0,1] row_mask:0xf bank_mask:0xf
	s_waitcnt lgkmcnt(0)
	v_add_f32_e32 v98, v98, v99
	s_nop 1
	v_mov_b32_dpp v99, v98 row_half_mirror row_mask:0xf bank_mask:0xf
	s_waitcnt lgkmcnt(0)
	v_add_f32_e32 v98, v98, v99
	s_nop 1
	v_mov_b32_dpp v99, v98 row_mirror row_mask:0xf bank_mask:0xf
	s_waitcnt lgkmcnt(0)
	v_add_f32_e32 v98, v98, v99
	v_mov_b32_e32 v99, v98
	s_nop 1
	v_permlane16_swap_b32_e32 v98, v99
	s_waitcnt lgkmcnt(0)
	v_add_f32_e32 v98, v98, v99
	v_fmamk_f32 v98, v98, 0x3c000000, v179
	v_cmp_gt_f32_e32 vcc, s4, v98
	v_mul_f32_e32 v99, 0x4f800000, v98
	s_nop 0
	v_cndmask_b32_e32 v98, v98, v99, vcc
	v_sqrt_f32_e32 v99, v98
	s_nop 0
	v_add_u32_e32 v100, -1, v99
	v_fma_f32 v102, -v100, v99, v98
	v_cmp_ge_f32_e64 s[0:1], 0, v102
	v_add_u32_e32 v102, 1, v99
	s_nop 0
	v_cndmask_b32_e64 v100, v99, v100, s[0:1]
	v_fma_f32 v99, -v102, v99, v98
	v_cmp_lt_f32_e64 s[0:1], 0, v99
	s_nop 1
	v_cndmask_b32_e64 v99, v100, v102, s[0:1]
	v_mul_f32_e32 v100, 0x37800000, v99
	v_cndmask_b32_e32 v99, v99, v100, vcc
	v_cmp_class_f32_e32 vcc, v98, v180
	s_nop 1
	v_cndmask_b32_e32 v98, v99, v98, vcc
	v_div_scale_f32 v99, s[0:1], v98, v98, 1.0
	v_rcp_f32_e32 v100, v99
	s_nop 0
	v_fma_f32 v102, -v99, v100, 1.0
	v_fmac_f32_e32 v100, v102, v100
	v_div_scale_f32 v102, vcc, 1.0, v98, 1.0
	v_mul_f32_e32 v103, v102, v100
	v_fma_f32 v104, -v99, v103, v102
	v_fmac_f32_e32 v103, v104, v100
	v_fma_f32 v99, -v99, v103, v102
	v_div_fmas_f32 v99, v99, v100, v103
	v_div_fixup_f32 v100, v99, v98, 1.0
	v_lshlrev_b64 v[98:99], 12, v[30:31]
	v_mul_f32_e32 v31, v88, v100
	v_mul_f32_e32 v31, v34, v31
	v_bfe_u32 v88, v31, 16, 1
	v_lshl_add_u64 v[98:99], v[4:5], 0, v[98:99]
	v_add3_u32 v31, v31, v88, s70
	global_store_short_d16_hi v[98:99], v31, off
	v_mul_f32_e32 v31, v97, v100
	v_mul_f32_e32 v31, v35, v31
	v_bfe_u32 v88, v31, 16, 1
	v_mul_f32_e32 v9, v9, v100
	v_add3_u32 v31, v31, v88, s70
	v_mul_f32_e32 v9, v36, v9
	global_store_short_d16_hi v[98:99], v31, off offset:64
	v_bfe_u32 v31, v9, 16, 1
	v_add3_u32 v9, v9, v31, s70
	global_store_short_d16_hi v[98:99], v9, off offset:128
	v_mul_f32_e32 v9, v101, v100
	v_mul_f32_e32 v9, v37, v9
	v_bfe_u32 v31, v9, 16, 1
	v_add3_u32 v9, v9, v31, s70
	global_store_short_d16_hi v[98:99], v9, off offset:192
	v_or_b32_e32 v98, 1, v30
	v_add_u32_e32 v9, v98, v8
	v_lshl_add_u32 v9, v9, 7, v138
	v_lshl_add_u32 v9, v9, 2, 0
	ds_read2_b32 v[100:101], v9 offset1:32
	s_waitcnt lgkmcnt(0)
	v_fma_f32 v88, -v160, v101, v96
	ds_read2_b32 v[96:97], v9 offset0:64 offset1:96
	v_fma_f32 v31, -v160, v100, v95
	v_mul_f32_e32 v95, v88, v88
	v_fmac_f32_e32 v95, v31, v31
	s_waitcnt lgkmcnt(0)
	v_fma_f32 v9, -v160, v96, v93
	v_fmac_f32_e32 v95, v9, v9
	v_fma_f32 v93, -v160, v97, v94
	v_fmac_f32_e32 v95, v93, v93
	s_nop 1
	v_mov_b32_dpp v94, v95 quad_perm:[1,0,3,2] row_mask:0xf bank_mask:0xf
	s_waitcnt lgkmcnt(0)
	v_add_f32_e32 v94, v95, v94
	s_nop 1
	v_mov_b32_dpp v95, v94 quad_perm:[2,3,0,1] row_mask:0xf bank_mask:0xf
	s_waitcnt lgkmcnt(0)
	v_add_f32_e32 v94, v94, v95
	s_nop 1
	v_mov_b32_dpp v95, v94 row_half_mirror row_mask:0xf bank_mask:0xf
	s_waitcnt lgkmcnt(0)
	v_add_f32_e32 v94, v94, v95
	s_nop 1
	v_mov_b32_dpp v95, v94 row_mirror row_mask:0xf bank_mask:0xf
	s_waitcnt lgkmcnt(0)
; __device__ __forceinline__ unsigned f2bf(float f) { unsigned u = __builtin_bit_cast(unsigned, f); return (u + 0x7fffu + ((u >> 16) & 1u)) >> 16; }
; __device__ __forceinline__ int crow(int r, int hi) { return (r & 3) + 8 * (r >> 2) + 4 * hi; }
; __device__ __forceinline__ void attn_unit(const bf16* __restrict__ Qb, const bf16* __restrict__ Kh, const bf16* __restrict__ Vh, int klat0, int nlt, int kctx0, int NT,
;                                           float lam, float post, const float* __restrict__ subw, bf16* __restrict__ Ob, char* lds) {
;     ...
;     for (int r = 0; r < 16; ++r) { const int orow = crow(r, hi_e); float v[4]; float ss = 0.f;
; #pragma unroll
;       for (int d0 = 0; d0 < 4; ++d0) { v[d0] = o[d0][r] - lam * X[(wq_e * 32 + orow) * 128 + d0 * 32 + r32_e]; ss += v[d0] * v[d0]; }
;       ss += __shfl_xor(ss, 1); ss += __shfl_xor(ss, 2); ss += __shfl_xor(ss, 4); ss += __shfl_xor(ss, 8); ss += __shfl_xor(ss, 16);
;       const float rs = 1.0f / sqrtf(ss * (1.0f / 128.0f) + LN_EPS);
; #pragma unroll
;       for (int d0 = 0; d0 < 4; ++d0) Ow[(long)orow * DM + d0 * 32 + r32_e] = (bf16)f2bf(v[d0] * rs * sw[d0]); }
	v_add_f32_e32 v94, v94, v95
	v_mov_b32_e32 v95, v94
	s_nop 1
	v_permlane16_swap_b32_e32 v94, v95
	s_waitcnt lgkmcnt(0)
	v_add_f32_e32 v94, v94, v95
	v_fmamk_f32 v94, v94, 0x3c000000, v179
	v_cmp_gt_f32_e32 vcc, s4, v94
	v_mul_f32_e32 v95, 0x4f800000, v94
	s_nop 0
	v_cndmask_b32_e32 v94, v94, v95, vcc
	v_sqrt_f32_e32 v95, v94
	s_nop 0
	v_add_u32_e32 v96, -1, v95
	v_fma_f32 v97, -v96, v95, v94
	v_cmp_ge_f32_e64 s[0:1], 0, v97
	v_add_u32_e32 v97, 1, v95
	s_nop 0
	v_cndmask_b32_e64 v96, v95, v96, s[0:1]
	v_fma_f32 v95, -v97, v95, v94
	v_cmp_lt_f32_e64 s[0:1], 0, v95
	s_nop 1
	v_cndmask_b32_e64 v95, v96, v97, s[0:1]
	v_mul_f32_e32 v96, 0x37800000, v95
	v_cndmask_b32_e32 v95, v95, v96, vcc
	v_cmp_class_f32_e32 vcc, v94, v180
	s_nop 1
	v_cndmask_b32_e32 v94, v95, v94, vcc
	v_div_scale_f32 v95, s[0:1], v94, v94, 1.0
	v_rcp_f32_e32 v96, v95
	s_nop 0
	v_fma_f32 v97, -v95, v96, 1.0
	v_fmac_f32_e32 v96, v97, v96
	v_div_scale_f32 v97, vcc, 1.0, v94, 1.0
	v_mul_f32_e32 v99, v97, v96
	v_fma_f32 v100, -v95, v99, v97
	v_fmac_f32_e32 v99, v100, v96
	v_fma_f32 v95, -v95, v99, v97
	v_div_fmas_f32 v95, v95, v96, v99
	v_div_fixup_f32 v96, v95, v94, 1.0
	v_mul_f32_e32 v31, v31, v96
	v_ashrrev_i32_e32 v99, 31, v98
	v_mul_f32_e32 v31, v34, v31
	v_lshlrev_b64 v[94:95], 12, v[98:99]
	v_bfe_u32 v97, v31, 16, 1
	v_lshl_add_u64 v[94:95], v[4:5], 0, v[94:95]
	v_add3_u32 v31, v31, v97, s70
	global_store_short_d16_hi v[94:95], v31, off
	v_mul_f32_e32 v31, v88, v96
	v_mul_f32_e32 v31, v35, v31
	v_bfe_u32 v88, v31, 16, 1
	v_mul_f32_e32 v9, v9, v96
	v_add3_u32 v31, v31, v88, s70
	v_mul_f32_e32 v9, v36, v9
	global_store_short_d16_hi v[94:95], v31, off offset:64
	v_bfe_u32 v31, v9, 16, 1
	v_add3_u32 v9, v9, v31, s70
	global_store_short_d16_hi v[94:95], v9, off offset:128
	v_mul_f32_e32 v9, v93, v96
	v_mul_f32_e32 v9, v37, v9
	v_bfe_u32 v31, v9, 16, 1
	v_add3_u32 v9, v9, v31, s70
	v_or_b32_e32 v88, 2, v30
	global_store_short_d16_hi v[94:95], v9, off offset:192
	v_add_u32_e32 v9, v88, v8
	v_lshl_add_u32 v9, v9, 7, v138
	v_lshl_add_u32 v9, v9, 2, 0
	ds_read2_b32 v[94:95], v9 offset1:32
	v_or_b32_e32 v30, 3, v30
	s_waitcnt lgkmcnt(0)
	v_fma_f32 v31, -v160, v94, v91
	v_fma_f32 v91, -v160, v95, v92
	ds_read2_b32 v[92:93], v9 offset0:64 offset1:96
	v_mul_f32_e32 v94, v91, v91
	v_fmac_f32_e32 v94, v31, v31
	s_waitcnt lgkmcnt(0)
	v_fma_f32 v9, -v160, v92, v89
	v_fmac_f32_e32 v94, v9, v9
	v_fma_f32 v90, -v160, v93, v90
	v_fmac_f32_e32 v94, v90, v90
	s_nop 1
	v_mov_b32_dpp v89, v94 quad_perm:[1,0,3,2] row_mask:0xf bank_mask:0xf
	s_waitcnt lgkmcnt(0)
	v_add_f32_e32 v89, v94, v89
	s_nop 1
	v_mov_b32_dpp v92, v89 quad_perm:[2,3,0,1] row_mask:0xf bank_mask:0xf
	s_waitcnt lgkmcnt(0)
	v_add_f32_e32 v89, v89, v92
	s_nop 1
	v_mov_b32_dpp v92, v89 row_half_mirror row_mask:0xf bank_mask:0xf
	s_waitcnt lgkmcnt(0)
	v_add_f32_e32 v89, v89, v92
	s_nop 1
	v_mov_b32_dpp v92, v89 row_mirror row_mask:0xf bank_mask:0xf
	s_waitcnt lgkmcnt(0)
	v_add_f32_e32 v89, v89, v92
	v_mov_b32_e32 v92, v89
	s_nop 1
	v_permlane16_swap_b32_e32 v89, v92
	s_waitcnt lgkmcnt(0)
	v_add_f32_e32 v89, v89, v92
	v_fmamk_f32 v89, v89, 0x3c000000, v179
	v_cmp_gt_f32_e32 vcc, s4, v89
	v_mul_f32_e32 v92, 0x4f800000, v89
	s_nop 0
	v_cndmask_b32_e32 v89, v89, v92, vcc
	v_sqrt_f32_e32 v92, v89
	s_nop 0
	v_add_u32_e32 v93, -1, v92
	v_fma_f32 v94, -v93, v92, v89
	v_cmp_ge_f32_e64 s[0:1], 0, v94
	v_add_u32_e32 v94, 1, v92
	s_nop 0
	v_cndmask_b32_e64 v93, v92, v93, s[0:1]
	v_fma_f32 v92, -v94, v92, v89
	v_cmp_lt_f32_e64 s[0:1], 0, v92
	s_nop 1
	v_cndmask_b32_e64 v92, v93, v94, s[0:1]
	v_mul_f32_e32 v93, 0x37800000, v92
	v_cndmask_b32_e32 v92, v92, v93, vcc
	v_cmp_class_f32_e32 vcc, v89, v180
	s_nop 1
	v_cndmask_b32_e32 v89, v92, v89, vcc
	v_div_scale_f32 v92, s[0:1], v89, v89, 1.0
	v_rcp_f32_e32 v93, v92
	s_nop 0
	v_fma_f32 v94, -v92, v93, 1.0
	v_fmac_f32_e32 v93, v94, v93
	v_div_scale_f32 v94, vcc, 1.0, v89, 1.0
	v_mul_f32_e32 v95, v94, v93
	v_fma_f32 v96, -v92, v95, v94
	v_fmac_f32_e32 v95, v96, v93
	v_fma_f32 v92, -v92, v95, v94
	v_div_fmas_f32 v92, v92, v93, v95
	v_div_fixup_f32 v92, v92, v89, 1.0
	v_mul_f32_e32 v31, v31, v92
	v_ashrrev_i32_e32 v89, 31, v88
	v_mul_f32_e32 v31, v34, v31
	v_lshlrev_b64 v[88:89], 12, v[88:89]
	v_bfe_u32 v93, v31, 16, 1
	v_lshl_add_u64 v[88:89], v[4:5], 0, v[88:89]
	v_add3_u32 v31, v31, v93, s70
	global_store_short_d16_hi v[88:89], v31, off
	v_mul_f32_e32 v31, v91, v92
	v_mul_f32_e32 v31, v35, v31
	v_bfe_u32 v91, v31, 16, 1
	v_mul_f32_e32 v9, v9, v92
	v_add3_u32 v31, v31, v91, s70
	v_mul_f32_e32 v9, v36, v9
	global_store_short_d16_hi v[88:89], v31, off offset:64
	v_bfe_u32 v31, v9, 16, 1
	v_add3_u32 v9, v9, v31, s70
	global_store_short_d16_hi v[88:89], v9, off offset:128
	v_mul_f32_e32 v9, v90, v92
	v_mul_f32_e32 v9, v37, v9
	v_bfe_u32 v31, v9, 16, 1
	v_add3_u32 v9, v9, v31, s70
	global_store_short_d16_hi v[88:89], v9, off offset:192
	v_add_u32_e32 v9, v30, v8
	v_lshl_add_u32 v9, v9, 7, v138
	v_lshl_add_u32 v9, v9, 2, 0
	ds_read2_b32 v[88:89], v9 offset1:32
	s_waitcnt lgkmcnt(0)
	v_fma_f32 v88, -v160, v88, v86
	v_fma_f32 v89, -v160, v89, v87
	ds_read2_b32 v[86:87], v9 offset0:64 offset1:96
	v_mul_f32_e32 v31, v89, v89
	v_fmac_f32_e32 v31, v88, v88
	s_waitcnt lgkmcnt(0)
	v_fma_f32 v9, -v160, v86, v84
	v_fmac_f32_e32 v31, v9, v9
	v_fma_f32 v84, -v160, v87, v85
	v_fmac_f32_e32 v31, v84, v84
	s_nop 1
	v_mov_b32_dpp v85, v31 quad_perm:[1,0,3,2] row_mask:0xf bank_mask:0xf
	s_waitcnt lgkmcnt(0)
	v_add_f32_e32 v31, v31, v85
	s_nop 1
	v_mov_b32_dpp v85, v31 quad_perm:[2,3,0,1] row_mask:0xf bank_mask:0xf
	s_waitcnt lgkmcnt(0)
	v_add_f32_e32 v31, v31, v85
	s_nop 1
	v_mov_b32_dpp v85, v31 row_half_mirror row_mask:0xf bank_mask:0xf
	s_waitcnt lgkmcnt(0)
; __device__ __forceinline__ unsigned f2bf(float f) { unsigned u = __builtin_bit_cast(unsigned, f); return (u + 0x7fffu + ((u >> 16) & 1u)) >> 16; }
; __device__ __forceinline__ int crow(int r, int hi) { return (r & 3) + 8 * (r >> 2) + 4 * hi; }
; __device__ __forceinline__ void attn_unit(const bf16* __restrict__ Qb, const bf16* __restrict__ Kh, const bf16* __restrict__ Vh, int klat0, int nlt, int kctx0, int NT,
;                                           float lam, float post, const float* __restrict__ subw, bf16* __restrict__ Ob, char* lds) {
;     ...
;     for (int r = 0; r < 16; ++r) { const int orow = crow(r, hi_e); float v[4]; float ss = 0.f;
; #pragma unroll
;       for (int d0 = 0; d0 < 4; ++d0) { v[d0] = o[d0][r] - lam * X[(wq_e * 32 + orow) * 128 + d0 * 32 + r32_e]; ss += v[d0] * v[d0]; }
;       ss += __shfl_xor(ss, 1); ss += __shfl_xor(ss, 2); ss += __shfl_xor(ss, 4); ss += __shfl_xor(ss, 8); ss += __shfl_xor(ss, 16);
;       const float rs = 1.0f / sqrtf(ss * (1.0f / 128.0f) + LN_EPS);
; #pragma unroll
;       for (int d0 = 0; d0 < 4; ++d0) Ow[(long)orow * DM + d0 * 32 + r32_e] = (bf16)f2bf(v[d0] * rs * sw[d0]); }
	v_add_f32_e32 v31, v31, v85
	s_nop 1
	v_mov_b32_dpp v85, v31 row_mirror row_mask:0xf bank_mask:0xf
	s_waitcnt lgkmcnt(0)
	v_add_f32_e32 v31, v31, v85
	v_mov_b32_e32 v85, v31
	s_nop 1
	v_permlane16_swap_b32_e32 v31, v85
	s_waitcnt lgkmcnt(0)
	v_add_f32_e32 v31, v31, v85
	v_fmamk_f32 v31, v31, 0x3c000000, v179
	v_cmp_gt_f32_e32 vcc, s4, v31
	v_mul_f32_e32 v85, 0x4f800000, v31
	s_nop 0
	v_cndmask_b32_e32 v31, v31, v85, vcc
	v_sqrt_f32_e32 v85, v31
	s_nop 0
	v_add_u32_e32 v86, -1, v85
	v_fma_f32 v87, -v86, v85, v31
	v_cmp_ge_f32_e64 s[0:1], 0, v87
	v_add_u32_e32 v87, 1, v85
	s_nop 0
	v_cndmask_b32_e64 v86, v85, v86, s[0:1]
	v_fma_f32 v85, -v87, v85, v31
	v_cmp_lt_f32_e64 s[0:1], 0, v85
	s_nop 1
	v_cndmask_b32_e64 v85, v86, v87, s[0:1]
	v_mul_f32_e32 v86, 0x37800000, v85
	v_cndmask_b32_e32 v85, v85, v86, vcc
	v_cmp_class_f32_e32 vcc, v31, v180
	s_nop 1
	v_cndmask_b32_e32 v31, v85, v31, vcc
	v_div_scale_f32 v85, s[0:1], v31, v31, 1.0
	v_rcp_f32_e32 v86, v85
	s_nop 0
	v_fma_f32 v87, -v85, v86, 1.0
	v_fmac_f32_e32 v86, v87, v86
	v_div_scale_f32 v87, vcc, 1.0, v31, 1.0
	v_mul_f32_e32 v90, v87, v86
	v_fma_f32 v91, -v85, v90, v87
	v_fmac_f32_e32 v90, v91, v86
	v_fma_f32 v85, -v85, v90, v87
	v_div_fmas_f32 v85, v85, v86, v90
	v_div_fixup_f32 v85, v85, v31, 1.0
	v_mul_f32_e32 v86, v88, v85
	v_ashrrev_i32_e32 v31, 31, v30
	v_mul_f32_e32 v86, v34, v86
	v_lshlrev_b64 v[30:31], 12, v[30:31]
	v_bfe_u32 v87, v86, 16, 1
	v_lshl_add_u64 v[30:31], v[4:5], 0, v[30:31]
	v_add3_u32 v86, v86, v87, s70
	global_store_short_d16_hi v[30:31], v86, off
	v_mul_f32_e32 v86, v89, v85
	v_mul_f32_e32 v86, v35, v86
	v_bfe_u32 v87, v86, 16, 1
	v_mul_f32_e32 v9, v9, v85
	v_add3_u32 v86, v86, v87, s70
	v_mul_f32_e32 v9, v36, v9
	global_store_short_d16_hi v[30:31], v86, off offset:64
	v_bfe_u32 v86, v9, 16, 1
	v_add3_u32 v9, v9, v86, s70
	global_store_short_d16_hi v[30:31], v9, off offset:128
	v_mul_f32_e32 v9, v84, v85
	v_mul_f32_e32 v9, v37, v9
	v_bfe_u32 v84, v9, 16, 1
	v_add3_u32 v9, v9, v84, s70
	global_store_short_d16_hi v[30:31], v9, off offset:192
	v_add_u32_e32 v9, v28, v8
	v_lshl_add_u32 v9, v9, 7, v138
	v_lshl_add_u32 v9, v9, 2, 0
	ds_read2_b32 v[30:31], v9 offset1:32
	v_lshlrev_b64 v[28:29], 12, v[28:29]
	v_lshl_add_u64 v[28:29], v[4:5], 0, v[28:29]
	s_waitcnt lgkmcnt(0)
	v_fma_f32 v82, -v160, v30, v82
	v_fma_f32 v83, -v160, v31, v83
	ds_read2_b32 v[30:31], v9 offset0:64 offset1:96
	v_mul_f32_e32 v84, v83, v83
	v_fmac_f32_e32 v84, v82, v82
	s_waitcnt lgkmcnt(0)
	v_fma_f32 v9, -v160, v30, v65
	v_fmac_f32_e32 v84, v9, v9
	v_fma_f32 v30, -v160, v31, v81
	v_fmac_f32_e32 v84, v30, v30
	s_nop 1
	v_mov_b32_dpp v31, v84 quad_perm:[1,0,3,2] row_mask:0xf bank_mask:0xf
	s_waitcnt lgkmcnt(0)
	v_add_f32_e32 v31, v84, v31
	s_nop 1
	v_mov_b32_dpp v65, v31 quad_perm:[2,3,0,1] row_mask:0xf bank_mask:0xf
	s_waitcnt lgkmcnt(0)
	v_add_f32_e32 v31, v31, v65
	s_nop 1
	v_mov_b32_dpp v65, v31 row_half_mirror row_mask:0xf bank_mask:0xf
	s_waitcnt lgkmcnt(0)
	v_add_f32_e32 v31, v31, v65
	s_nop 1
	v_mov_b32_dpp v65, v31 row_mirror row_mask:0xf bank_mask:0xf
	s_waitcnt lgkmcnt(0)
	v_add_f32_e32 v31, v31, v65
	v_mov_b32_e32 v65, v31
	s_nop 1
	v_permlane16_swap_b32_e32 v31, v65
	s_waitcnt lgkmcnt(0)
	v_add_f32_e32 v31, v31, v65
	v_fmamk_f32 v31, v31, 0x3c000000, v179
	v_cmp_gt_f32_e32 vcc, s4, v31
	v_mul_f32_e32 v65, 0x4f800000, v31
	s_nop 0
	v_cndmask_b32_e32 v31, v31, v65, vcc
	v_sqrt_f32_e32 v65, v31
	s_nop 0
	v_add_u32_e32 v81, -1, v65
	v_fma_f32 v84, -v81, v65, v31
	v_cmp_ge_f32_e64 s[0:1], 0, v84
	v_add_u32_e32 v84, 1, v65
	s_nop 0
	v_cndmask_b32_e64 v81, v65, v81, s[0:1]
	v_fma_f32 v65, -v84, v65, v31
	v_cmp_lt_f32_e64 s[0:1], 0, v65
	s_nop 1
	v_cndmask_b32_e64 v65, v81, v84, s[0:1]
	v_mul_f32_e32 v81, 0x37800000, v65
	v_cndmask_b32_e32 v65, v65, v81, vcc
	v_cmp_class_f32_e32 vcc, v31, v180
	s_nop 1
	v_cndmask_b32_e32 v31, v65, v31, vcc
	v_div_scale_f32 v65, s[0:1], v31, v31, 1.0
	v_rcp_f32_e32 v81, v65
	s_nop 0
	v_fma_f32 v84, -v65, v81, 1.0
	v_fmac_f32_e32 v81, v84, v81
	v_div_scale_f32 v84, vcc, 1.0, v31, 1.0
	v_mul_f32_e32 v85, v84, v81
	v_fma_f32 v86, -v65, v85, v84
	v_fmac_f32_e32 v85, v86, v81
	v_fma_f32 v65, -v65, v85, v84
	v_div_fmas_f32 v65, v65, v81, v85
	v_div_fixup_f32 v31, v65, v31, 1.0
	v_mul_f32_e32 v65, v82, v31
	v_mul_f32_e32 v65, v34, v65
	v_bfe_u32 v81, v65, 16, 1
	v_add3_u32 v65, v65, v81, s70
	global_store_short_d16_hi v[28:29], v65, off
	v_mul_f32_e32 v65, v83, v31
	v_mul_f32_e32 v65, v35, v65
	v_bfe_u32 v81, v65, 16, 1
	v_mul_f32_e32 v9, v9, v31
	v_add3_u32 v65, v65, v81, s70
	v_mul_f32_e32 v9, v36, v9
	global_store_short_d16_hi v[28:29], v65, off offset:64
	v_bfe_u32 v65, v9, 16, 1
	v_add3_u32 v9, v9, v65, s70
	global_store_short_d16_hi v[28:29], v9, off offset:128
	v_mul_f32_e32 v9, v30, v31
	v_mul_f32_e32 v9, v37, v9
	v_bfe_u32 v30, v9, 16, 1
	v_add3_u32 v9, v9, v30, s70
	global_store_short_d16_hi v[28:29], v9, off offset:192
	v_add_u32_e32 v9, v26, v8
	v_lshl_add_u32 v9, v9, 7, v138
	v_lshl_add_u32 v9, v9, 2, 0
	ds_read2_b32 v[28:29], v9 offset1:32
	v_lshlrev_b64 v[26:27], 12, v[26:27]
	v_lshl_add_u64 v[26:27], v[4:5], 0, v[26:27]
	s_waitcnt lgkmcnt(0)
	v_fma_f32 v30, -v160, v28, v79
	v_fma_f32 v31, -v160, v29, v80
	ds_read2_b32 v[28:29], v9 offset0:64 offset1:96
	v_mul_f32_e32 v65, v31, v31
	v_fmac_f32_e32 v65, v30, v30
	s_waitcnt lgkmcnt(0)
	v_fma_f32 v9, -v160, v28, v63
	v_fmac_f32_e32 v65, v9, v9
	v_fma_f32 v28, -v160, v29, v64
	v_fmac_f32_e32 v65, v28, v28
	s_nop 1
	v_mov_b32_dpp v29, v65 quad_perm:[1,0,3,2] row_mask:0xf bank_mask:0xf
	s_waitcnt lgkmcnt(0)
	v_add_f32_e32 v29, v65, v29
	s_nop 1
	v_mov_b32_dpp v63, v29 quad_perm:[2,3,0,1] row_mask:0xf bank_mask:0xf
	s_waitcnt lgkmcnt(0)
; __device__ __forceinline__ unsigned f2bf(float f) { unsigned u = __builtin_bit_cast(unsigned, f); return (u + 0x7fffu + ((u >> 16) & 1u)) >> 16; }
; __device__ __forceinline__ int crow(int r, int hi) { return (r & 3) + 8 * (r >> 2) + 4 * hi; }
; __device__ __forceinline__ void attn_unit(const bf16* __restrict__ Qb, const bf16* __restrict__ Kh, const bf16* __restrict__ Vh, int klat0, int nlt, int kctx0, int NT,
;                                           float lam, float post, const float* __restrict__ subw, bf16* __restrict__ Ob, char* lds) {
;     ...
;     for (int r = 0; r < 16; ++r) { const int orow = crow(r, hi_e); float v[4]; float ss = 0.f;
; #pragma unroll
;       for (int d0 = 0; d0 < 4; ++d0) { v[d0] = o[d0][r] - lam * X[(wq_e * 32 + orow) * 128 + d0 * 32 + r32_e]; ss += v[d0] * v[d0]; }
;       ss += __shfl_xor(ss, 1); ss += __shfl_xor(ss, 2); ss += __shfl_xor(ss, 4); ss += __shfl_xor(ss, 8); ss += __shfl_xor(ss, 16);
;       const float rs = 1.0f / sqrtf(ss * (1.0f / 128.0f) + LN_EPS);
; #pragma unroll
;       for (int d0 = 0; d0 < 4; ++d0) Ow[(long)orow * DM + d0 * 32 + r32_e] = (bf16)f2bf(v[d0] * rs * sw[d0]); }
	v_add_f32_e32 v29, v29, v63
	s_nop 1
	v_mov_b32_dpp v63, v29 row_half_mirror row_mask:0xf bank_mask:0xf
	s_waitcnt lgkmcnt(0)
	v_add_f32_e32 v29, v29, v63
	s_nop 1
	v_mov_b32_dpp v63, v29 row_mirror row_mask:0xf bank_mask:0xf
	s_waitcnt lgkmcnt(0)
	v_add_f32_e32 v29, v29, v63
	v_mov_b32_e32 v63, v29
	s_nop 1
	v_permlane16_swap_b32_e32 v29, v63
	s_waitcnt lgkmcnt(0)
	v_add_f32_e32 v29, v29, v63
	v_fmamk_f32 v29, v29, 0x3c000000, v179
	v_cmp_gt_f32_e32 vcc, s4, v29
	v_mul_f32_e32 v63, 0x4f800000, v29
	s_nop 0
	v_cndmask_b32_e32 v29, v29, v63, vcc
	v_sqrt_f32_e32 v63, v29
	s_nop 0
	v_add_u32_e32 v64, -1, v63
	v_fma_f32 v65, -v64, v63, v29
	v_cmp_ge_f32_e64 s[0:1], 0, v65
	v_add_u32_e32 v65, 1, v63
	s_nop 0
	v_cndmask_b32_e64 v64, v63, v64, s[0:1]
	v_fma_f32 v63, -v65, v63, v29
	v_cmp_lt_f32_e64 s[0:1], 0, v63
	s_nop 1
	v_cndmask_b32_e64 v63, v64, v65, s[0:1]
	v_mul_f32_e32 v64, 0x37800000, v63
	v_cndmask_b32_e32 v63, v63, v64, vcc
	v_cmp_class_f32_e32 vcc, v29, v180
	s_nop 1
	v_cndmask_b32_e32 v29, v63, v29, vcc
	v_div_scale_f32 v63, s[0:1], v29, v29, 1.0
	v_rcp_f32_e32 v64, v63
	s_nop 0
	v_fma_f32 v65, -v63, v64, 1.0
	v_fmac_f32_e32 v64, v65, v64
	v_div_scale_f32 v65, vcc, 1.0, v29, 1.0
	v_mul_f32_e32 v79, v65, v64
	v_fma_f32 v80, -v63, v79, v65
	v_fmac_f32_e32 v79, v80, v64
	v_fma_f32 v63, -v63, v79, v65
	v_div_fmas_f32 v63, v63, v64, v79
	v_div_fixup_f32 v29, v63, v29, 1.0
	v_mul_f32_e32 v30, v30, v29
	v_mul_f32_e32 v30, v34, v30
	v_bfe_u32 v63, v30, 16, 1
	v_add3_u32 v30, v30, v63, s70
	global_store_short_d16_hi v[26:27], v30, off
	v_mul_f32_e32 v30, v31, v29
	v_mul_f32_e32 v30, v35, v30
	v_bfe_u32 v31, v30, 16, 1
	v_mul_f32_e32 v9, v9, v29
	v_add3_u32 v30, v30, v31, s70
	v_mul_f32_e32 v9, v36, v9
	global_store_short_d16_hi v[26:27], v30, off offset:64
	v_bfe_u32 v30, v9, 16, 1
	v_add3_u32 v9, v9, v30, s70
	global_store_short_d16_hi v[26:27], v9, off offset:128
	v_mul_f32_e32 v9, v28, v29
	v_mul_f32_e32 v9, v37, v9
	v_bfe_u32 v28, v9, 16, 1
	v_add3_u32 v9, v9, v28, s70
	global_store_short_d16_hi v[26:27], v9, off offset:192
	v_add_u32_e32 v9, v24, v8
	v_lshl_add_u32 v9, v9, 7, v138
	v_lshl_add_u32 v9, v9, 2, 0
	ds_read2_b32 v[26:27], v9 offset1:32
	v_lshlrev_b64 v[24:25], 12, v[24:25]
	v_lshl_add_u64 v[24:25], v[4:5], 0, v[24:25]
	s_waitcnt lgkmcnt(0)
	v_fma_f32 v28, -v160, v26, v77
	v_fma_f32 v29, -v160, v27, v78
	ds_read2_b32 v[26:27], v9 offset0:64 offset1:96
	v_mul_f32_e32 v30, v29, v29
	v_fmac_f32_e32 v30, v28, v28
	s_waitcnt lgkmcnt(0)
	v_fma_f32 v9, -v160, v26, v61
	v_fmac_f32_e32 v30, v9, v9
	v_fma_f32 v26, -v160, v27, v62
	v_fmac_f32_e32 v30, v26, v26
	s_nop 1
	v_mov_b32_dpp v27, v30 quad_perm:[1,0,3,2] row_mask:0xf bank_mask:0xf
	s_waitcnt lgkmcnt(0)
	v_add_f32_e32 v27, v30, v27
	s_nop 1
	v_mov_b32_dpp v30, v27 quad_perm:[2,3,0,1] row_mask:0xf bank_mask:0xf
	s_waitcnt lgkmcnt(0)
	v_add_f32_e32 v27, v27, v30
	s_nop 1
	v_mov_b32_dpp v30, v27 row_half_mirror row_mask:0xf bank_mask:0xf
	s_waitcnt lgkmcnt(0)
	v_add_f32_e32 v27, v27, v30
	s_nop 1
	v_mov_b32_dpp v30, v27 row_mirror row_mask:0xf bank_mask:0xf
	s_waitcnt lgkmcnt(0)
	v_add_f32_e32 v27, v27, v30
	v_mov_b32_e32 v30, v27
	s_nop 1
	v_permlane16_swap_b32_e32 v27, v30
	s_waitcnt lgkmcnt(0)
	v_add_f32_e32 v27, v27, v30
	v_fmamk_f32 v27, v27, 0x3c000000, v179
	v_cmp_gt_f32_e32 vcc, s4, v27
	v_mul_f32_e32 v30, 0x4f800000, v27
	s_nop 0
	v_cndmask_b32_e32 v27, v27, v30, vcc
	v_sqrt_f32_e32 v30, v27
	s_nop 0
	v_add_u32_e32 v31, -1, v30
	v_fma_f32 v61, -v31, v30, v27
	v_cmp_ge_f32_e64 s[0:1], 0, v61
	v_add_u32_e32 v61, 1, v30
	s_nop 0
	v_cndmask_b32_e64 v31, v30, v31, s[0:1]
	v_fma_f32 v30, -v61, v30, v27
	v_cmp_lt_f32_e64 s[0:1], 0, v30
	s_nop 1
	v_cndmask_b32_e64 v30, v31, v61, s[0:1]
	v_mul_f32_e32 v31, 0x37800000, v30
	v_cndmask_b32_e32 v30, v30, v31, vcc
	v_cmp_class_f32_e32 vcc, v27, v180
	s_nop 1
	v_cndmask_b32_e32 v27, v30, v27, vcc
	v_div_scale_f32 v30, s[0:1], v27, v27, 1.0
	v_rcp_f32_e32 v31, v30
	s_nop 0
	v_fma_f32 v61, -v30, v31, 1.0
	v_fmac_f32_e32 v31, v61, v31
	v_div_scale_f32 v61, vcc, 1.0, v27, 1.0
	v_mul_f32_e32 v62, v61, v31
	v_fma_f32 v63, -v30, v62, v61
	v_fmac_f32_e32 v62, v63, v31
	v_fma_f32 v30, -v30, v62, v61
	v_div_fmas_f32 v30, v30, v31, v62
	v_div_fixup_f32 v27, v30, v27, 1.0
	v_mul_f32_e32 v28, v28, v27
	v_mul_f32_e32 v28, v34, v28
	v_bfe_u32 v30, v28, 16, 1
	v_add3_u32 v28, v28, v30, s70
	global_store_short_d16_hi v[24:25], v28, off
	v_mul_f32_e32 v28, v29, v27
	v_mul_f32_e32 v28, v35, v28
	v_bfe_u32 v29, v28, 16, 1
	v_mul_f32_e32 v9, v9, v27
	v_add3_u32 v28, v28, v29, s70
	v_mul_f32_e32 v9, v36, v9
	global_store_short_d16_hi v[24:25], v28, off offset:64
	v_bfe_u32 v28, v9, 16, 1
	v_add3_u32 v9, v9, v28, s70
	global_store_short_d16_hi v[24:25], v9, off offset:128
	v_mul_f32_e32 v9, v26, v27
	v_mul_f32_e32 v9, v37, v9
	v_bfe_u32 v26, v9, 16, 1
	v_add3_u32 v9, v9, v26, s70
	global_store_short_d16_hi v[24:25], v9, off offset:192
	v_add_u32_e32 v9, v22, v8
	v_lshl_add_u32 v9, v9, 7, v138
	v_lshl_add_u32 v9, v9, 2, 0
	ds_read2_b32 v[24:25], v9 offset1:32
	v_lshlrev_b64 v[22:23], 12, v[22:23]
	v_lshl_add_u64 v[22:23], v[4:5], 0, v[22:23]
	s_waitcnt lgkmcnt(0)
	v_fma_f32 v26, -v160, v24, v75
	v_fma_f32 v27, -v160, v25, v76
	ds_read2_b32 v[24:25], v9 offset0:64 offset1:96
	v_mul_f32_e32 v28, v27, v27
	v_fmac_f32_e32 v28, v26, v26
	s_waitcnt lgkmcnt(0)
	v_fma_f32 v9, -v160, v24, v60
	v_fmac_f32_e32 v28, v9, v9
	v_fma_f32 v24, -v160, v25, v49
	v_fmac_f32_e32 v28, v24, v24
	s_nop 1
	v_mov_b32_dpp v25, v28 quad_perm:[1,0,3,2] row_mask:0xf bank_mask:0xf
	s_waitcnt lgkmcnt(0)
	v_add_f32_e32 v25, v28, v25
	s_nop 1
	v_mov_b32_dpp v28, v25 quad_perm:[2,3,0,1] row_mask:0xf bank_mask:0xf
	s_waitcnt lgkmcnt(0)
; __device__ __forceinline__ unsigned f2bf(float f) { unsigned u = __builtin_bit_cast(unsigned, f); return (u + 0x7fffu + ((u >> 16) & 1u)) >> 16; }
; __device__ __forceinline__ int crow(int r, int hi) { return (r & 3) + 8 * (r >> 2) + 4 * hi; }
; __device__ __forceinline__ void attn_unit(const bf16* __restrict__ Qb, const bf16* __restrict__ Kh, const bf16* __restrict__ Vh, int klat0, int nlt, int kctx0, int NT,
;                                           float lam, float post, const float* __restrict__ subw, bf16* __restrict__ Ob, char* lds) {
;     ...
;     for (int r = 0; r < 16; ++r) { const int orow = crow(r, hi_e); float v[4]; float ss = 0.f;
; #pragma unroll
;       for (int d0 = 0; d0 < 4; ++d0) { v[d0] = o[d0][r] - lam * X[(wq_e * 32 + orow) * 128 + d0 * 32 + r32_e]; ss += v[d0] * v[d0]; }
;       ss += __shfl_xor(ss, 1); ss += __shfl_xor(ss, 2); ss += __shfl_xor(ss, 4); ss += __shfl_xor(ss, 8); ss += __shfl_xor(ss, 16);
;       const float rs = 1.0f / sqrtf(ss * (1.0f / 128.0f) + LN_EPS);
; #pragma unroll
;       for (int d0 = 0; d0 < 4; ++d0) Ow[(long)orow * DM + d0 * 32 + r32_e] = (bf16)f2bf(v[d0] * rs * sw[d0]); }
	v_add_f32_e32 v25, v25, v28
	s_nop 1
	v_mov_b32_dpp v28, v25 row_half_mirror row_mask:0xf bank_mask:0xf
	s_waitcnt lgkmcnt(0)
	v_add_f32_e32 v25, v25, v28
	s_nop 1
	v_mov_b32_dpp v28, v25 row_mirror row_mask:0xf bank_mask:0xf
	s_waitcnt lgkmcnt(0)
	v_add_f32_e32 v25, v25, v28
	v_mov_b32_e32 v28, v25
	s_nop 1
	v_permlane16_swap_b32_e32 v25, v28
	s_waitcnt lgkmcnt(0)
	v_add_f32_e32 v25, v25, v28
	v_fmamk_f32 v25, v25, 0x3c000000, v179
	v_cmp_gt_f32_e32 vcc, s4, v25
	v_mul_f32_e32 v28, 0x4f800000, v25
	s_nop 0
	v_cndmask_b32_e32 v25, v25, v28, vcc
	v_sqrt_f32_e32 v28, v25
	s_nop 0
	v_add_u32_e32 v29, -1, v28
	v_fma_f32 v30, -v29, v28, v25
	v_cmp_ge_f32_e64 s[0:1], 0, v30
	v_add_u32_e32 v30, 1, v28
	s_nop 0
	v_cndmask_b32_e64 v29, v28, v29, s[0:1]
	v_fma_f32 v28, -v30, v28, v25
	v_cmp_lt_f32_e64 s[0:1], 0, v28
	s_nop 1
	v_cndmask_b32_e64 v28, v29, v30, s[0:1]
	v_mul_f32_e32 v29, 0x37800000, v28
	v_cndmask_b32_e32 v28, v28, v29, vcc
	v_cmp_class_f32_e32 vcc, v25, v180
	s_nop 1
	v_cndmask_b32_e32 v25, v28, v25, vcc
	v_div_scale_f32 v28, s[0:1], v25, v25, 1.0
	v_rcp_f32_e32 v29, v28
	s_nop 0
	v_fma_f32 v30, -v28, v29, 1.0
	v_fmac_f32_e32 v29, v30, v29
	v_div_scale_f32 v30, vcc, 1.0, v25, 1.0
	v_mul_f32_e32 v31, v30, v29
	v_fma_f32 v49, -v28, v31, v30
	v_fmac_f32_e32 v31, v49, v29
	v_fma_f32 v28, -v28, v31, v30
	v_div_fmas_f32 v28, v28, v29, v31
	v_div_fixup_f32 v25, v28, v25, 1.0
	v_mul_f32_e32 v26, v26, v25
	v_mul_f32_e32 v26, v34, v26
	v_bfe_u32 v28, v26, 16, 1
	v_add3_u32 v26, v26, v28, s70
	global_store_short_d16_hi v[22:23], v26, off
	v_mul_f32_e32 v26, v27, v25
	v_mul_f32_e32 v26, v35, v26
	v_bfe_u32 v27, v26, 16, 1
	v_mul_f32_e32 v9, v9, v25
	v_add3_u32 v26, v26, v27, s70
	v_mul_f32_e32 v9, v36, v9
	global_store_short_d16_hi v[22:23], v26, off offset:64
	v_bfe_u32 v26, v9, 16, 1
	v_add3_u32 v9, v9, v26, s70
	global_store_short_d16_hi v[22:23], v9, off offset:128
	v_mul_f32_e32 v9, v24, v25
	v_mul_f32_e32 v9, v37, v9
	v_bfe_u32 v24, v9, 16, 1
	v_add3_u32 v9, v9, v24, s70
	global_store_short_d16_hi v[22:23], v9, off offset:192
	v_add_u32_e32 v9, v20, v8
	v_lshl_add_u32 v9, v9, 7, v138
	v_lshl_add_u32 v9, v9, 2, 0
	ds_read2_b32 v[22:23], v9 offset1:32
	v_lshlrev_b64 v[20:21], 12, v[20:21]
	v_lshl_add_u64 v[20:21], v[4:5], 0, v[20:21]
	s_waitcnt lgkmcnt(0)
	v_fma_f32 v24, -v160, v22, v73
	v_fma_f32 v25, -v160, v23, v74
	ds_read2_b32 v[22:23], v9 offset0:64 offset1:96
	v_mul_f32_e32 v26, v25, v25
	v_fmac_f32_e32 v26, v24, v24
	s_waitcnt lgkmcnt(0)
	v_fma_f32 v9, -v160, v22, v59
	v_fmac_f32_e32 v26, v9, v9
	v_fma_f32 v22, -v160, v23, v48
	v_fmac_f32_e32 v26, v22, v22
	s_nop 1
	v_mov_b32_dpp v23, v26 quad_perm:[1,0,3,2] row_mask:0xf bank_mask:0xf
	s_waitcnt lgkmcnt(0)
	v_add_f32_e32 v23, v26, v23
	s_nop 1
	v_mov_b32_dpp v26, v23 quad_perm:[2,3,0,1] row_mask:0xf bank_mask:0xf
	s_waitcnt lgkmcnt(0)
	v_add_f32_e32 v23, v23, v26
	s_nop 1
	v_mov_b32_dpp v26, v23 row_half_mirror row_mask:0xf bank_mask:0xf
	s_waitcnt lgkmcnt(0)
	v_add_f32_e32 v23, v23, v26
	s_nop 1
	v_mov_b32_dpp v26, v23 row_mirror row_mask:0xf bank_mask:0xf
	s_waitcnt lgkmcnt(0)
	v_add_f32_e32 v23, v23, v26
	v_mov_b32_e32 v26, v23
	s_nop 1
	v_permlane16_swap_b32_e32 v23, v26
	s_waitcnt lgkmcnt(0)
	v_add_f32_e32 v23, v23, v26
	v_fmamk_f32 v23, v23, 0x3c000000, v179
	v_cmp_gt_f32_e32 vcc, s4, v23
	v_mul_f32_e32 v26, 0x4f800000, v23
	s_nop 0
	v_cndmask_b32_e32 v23, v23, v26, vcc
	v_sqrt_f32_e32 v26, v23
	s_nop 0
	v_add_u32_e32 v27, -1, v26
	v_fma_f32 v28, -v27, v26, v23
	v_cmp_ge_f32_e64 s[0:1], 0, v28
	v_add_u32_e32 v28, 1, v26
	s_nop 0
	v_cndmask_b32_e64 v27, v26, v27, s[0:1]
	v_fma_f32 v26, -v28, v26, v23
	v_cmp_lt_f32_e64 s[0:1], 0, v26
	s_nop 1
	v_cndmask_b32_e64 v26, v27, v28, s[0:1]
	v_mul_f32_e32 v27, 0x37800000, v26
	v_cndmask_b32_e32 v26, v26, v27, vcc
	v_cmp_class_f32_e32 vcc, v23, v180
	s_nop 1
	v_cndmask_b32_e32 v23, v26, v23, vcc
	v_div_scale_f32 v26, s[0:1], v23, v23, 1.0
	v_rcp_f32_e32 v27, v26
	s_nop 0
	v_fma_f32 v28, -v26, v27, 1.0
	v_fmac_f32_e32 v27, v28, v27
	v_div_scale_f32 v28, vcc, 1.0, v23, 1.0
	v_mul_f32_e32 v29, v28, v27
	v_fma_f32 v30, -v26, v29, v28
	v_fmac_f32_e32 v29, v30, v27
	v_fma_f32 v26, -v26, v29, v28
	v_div_fmas_f32 v26, v26, v27, v29
	v_div_fixup_f32 v23, v26, v23, 1.0
	v_mul_f32_e32 v24, v24, v23
	v_mul_f32_e32 v24, v34, v24
	v_bfe_u32 v26, v24, 16, 1
	v_add3_u32 v24, v24, v26, s70
	global_store_short_d16_hi v[20:21], v24, off
	v_mul_f32_e32 v24, v25, v23
	v_mul_f32_e32 v24, v35, v24
	v_bfe_u32 v25, v24, 16, 1
	v_mul_f32_e32 v9, v9, v23
	v_add3_u32 v24, v24, v25, s70
	v_mul_f32_e32 v9, v36, v9
	global_store_short_d16_hi v[20:21], v24, off offset:64
	v_bfe_u32 v24, v9, 16, 1
	v_add3_u32 v9, v9, v24, s70
	global_store_short_d16_hi v[20:21], v9, off offset:128
	v_mul_f32_e32 v9, v22, v23
	v_mul_f32_e32 v9, v37, v9
	v_bfe_u32 v22, v9, 16, 1
	v_add3_u32 v9, v9, v22, s70
	global_store_short_d16_hi v[20:21], v9, off offset:192
	v_add_u32_e32 v9, v18, v8
	v_lshl_add_u32 v9, v9, 7, v138
	v_lshl_add_u32 v9, v9, 2, 0
	ds_read2_b32 v[20:21], v9 offset1:32
	v_lshlrev_b64 v[18:19], 12, v[18:19]
	v_lshl_add_u64 v[18:19], v[4:5], 0, v[18:19]
	s_waitcnt lgkmcnt(0)
	v_fma_f32 v22, -v160, v20, v72
	v_fma_f32 v23, -v160, v21, v58
	ds_read2_b32 v[20:21], v9 offset0:64 offset1:96
	v_mul_f32_e32 v24, v23, v23
	v_fmac_f32_e32 v24, v22, v22
	s_waitcnt lgkmcnt(0)
	v_fma_f32 v9, -v160, v20, v57
	v_fmac_f32_e32 v24, v9, v9
	v_fma_f32 v20, -v160, v21, v47
	v_fmac_f32_e32 v24, v20, v20
	s_nop 1
	v_mov_b32_dpp v21, v24 quad_perm:[1,0,3,2] row_mask:0xf bank_mask:0xf
	s_waitcnt lgkmcnt(0)
	v_add_f32_e32 v21, v24, v21
	s_nop 1
	v_mov_b32_dpp v24, v21 quad_perm:[2,3,0,1] row_mask:0xf bank_mask:0xf
	s_waitcnt lgkmcnt(0)
; __device__ __forceinline__ unsigned f2bf(float f) { unsigned u = __builtin_bit_cast(unsigned, f); return (u + 0x7fffu + ((u >> 16) & 1u)) >> 16; }
; __device__ __forceinline__ int crow(int r, int hi) { return (r & 3) + 8 * (r >> 2) + 4 * hi; }
; __device__ __forceinline__ void attn_unit(const bf16* __restrict__ Qb, const bf16* __restrict__ Kh, const bf16* __restrict__ Vh, int klat0, int nlt, int kctx0, int NT,
;                                           float lam, float post, const float* __restrict__ subw, bf16* __restrict__ Ob, char* lds) {
;     ...
;     for (int r = 0; r < 16; ++r) { const int orow = crow(r, hi_e); float v[4]; float ss = 0.f;
; #pragma unroll
;       for (int d0 = 0; d0 < 4; ++d0) { v[d0] = o[d0][r] - lam * X[(wq_e * 32 + orow) * 128 + d0 * 32 + r32_e]; ss += v[d0] * v[d0]; }
;       ss += __shfl_xor(ss, 1); ss += __shfl_xor(ss, 2); ss += __shfl_xor(ss, 4); ss += __shfl_xor(ss, 8); ss += __shfl_xor(ss, 16);
;       const float rs = 1.0f / sqrtf(ss * (1.0f / 128.0f) + LN_EPS);
; #pragma unroll
;       for (int d0 = 0; d0 < 4; ++d0) Ow[(long)orow * DM + d0 * 32 + r32_e] = (bf16)f2bf(v[d0] * rs * sw[d0]); }
	v_add_f32_e32 v21, v21, v24
	s_nop 1
	v_mov_b32_dpp v24, v21 row_half_mirror row_mask:0xf bank_mask:0xf
	s_waitcnt lgkmcnt(0)
	v_add_f32_e32 v21, v21, v24
	s_nop 1
	v_mov_b32_dpp v24, v21 row_mirror row_mask:0xf bank_mask:0xf
	s_waitcnt lgkmcnt(0)
	v_add_f32_e32 v21, v21, v24
	v_mov_b32_e32 v24, v21
	s_nop 1
	v_permlane16_swap_b32_e32 v21, v24
	s_waitcnt lgkmcnt(0)
	v_add_f32_e32 v21, v21, v24
	v_fmamk_f32 v21, v21, 0x3c000000, v179
	v_cmp_gt_f32_e32 vcc, s4, v21
	v_mul_f32_e32 v24, 0x4f800000, v21
	s_nop 0
	v_cndmask_b32_e32 v21, v21, v24, vcc
	v_sqrt_f32_e32 v24, v21
	s_nop 0
	v_add_u32_e32 v25, -1, v24
	v_fma_f32 v26, -v25, v24, v21
	v_cmp_ge_f32_e64 s[0:1], 0, v26
	v_add_u32_e32 v26, 1, v24
	s_nop 0
	v_cndmask_b32_e64 v25, v24, v25, s[0:1]
	v_fma_f32 v24, -v26, v24, v21
	v_cmp_lt_f32_e64 s[0:1], 0, v24
	s_nop 1
	v_cndmask_b32_e64 v24, v25, v26, s[0:1]
	v_mul_f32_e32 v25, 0x37800000, v24
	v_cndmask_b32_e32 v24, v24, v25, vcc
	v_cmp_class_f32_e32 vcc, v21, v180
	s_nop 1
	v_cndmask_b32_e32 v21, v24, v21, vcc
	v_div_scale_f32 v24, s[0:1], v21, v21, 1.0
	v_rcp_f32_e32 v25, v24
	s_nop 0
	v_fma_f32 v26, -v24, v25, 1.0
	v_fmac_f32_e32 v25, v26, v25
	v_div_scale_f32 v26, vcc, 1.0, v21, 1.0
	v_mul_f32_e32 v27, v26, v25
	v_fma_f32 v28, -v24, v27, v26
	v_fmac_f32_e32 v27, v28, v25
	v_fma_f32 v24, -v24, v27, v26
	v_div_fmas_f32 v24, v24, v25, v27
	v_div_fixup_f32 v21, v24, v21, 1.0
	v_mul_f32_e32 v22, v22, v21
	v_mul_f32_e32 v22, v34, v22
	v_bfe_u32 v24, v22, 16, 1
	v_add3_u32 v22, v22, v24, s70
	global_store_short_d16_hi v[18:19], v22, off
	v_mul_f32_e32 v22, v23, v21
	v_mul_f32_e32 v22, v35, v22
	v_bfe_u32 v23, v22, 16, 1
	v_mul_f32_e32 v9, v9, v21
	v_add3_u32 v22, v22, v23, s70
	v_mul_f32_e32 v9, v36, v9
	global_store_short_d16_hi v[18:19], v22, off offset:64
	v_bfe_u32 v22, v9, 16, 1
	v_add3_u32 v9, v9, v22, s70
	global_store_short_d16_hi v[18:19], v9, off offset:128
	v_mul_f32_e32 v9, v20, v21
	v_mul_f32_e32 v9, v37, v9
	v_bfe_u32 v20, v9, 16, 1
	v_add3_u32 v9, v9, v20, s70
	global_store_short_d16_hi v[18:19], v9, off offset:192
	v_add_u32_e32 v9, v16, v8
	v_lshl_add_u32 v9, v9, 7, v138
	v_lshl_add_u32 v9, v9, 2, 0
	ds_read2_b32 v[18:19], v9 offset1:32
	v_lshlrev_b64 v[16:17], 12, v[16:17]
	v_lshl_add_u64 v[16:17], v[4:5], 0, v[16:17]
	s_waitcnt lgkmcnt(0)
	v_fma_f32 v20, -v160, v18, v71
	v_fma_f32 v21, -v160, v19, v56
	ds_read2_b32 v[18:19], v9 offset0:64 offset1:96
	v_mul_f32_e32 v22, v21, v21
	v_fmac_f32_e32 v22, v20, v20
	s_waitcnt lgkmcnt(0)
	v_fma_f32 v9, -v160, v18, v55
	v_fmac_f32_e32 v22, v9, v9
	v_fma_f32 v18, -v160, v19, v46
	v_fmac_f32_e32 v22, v18, v18
	s_nop 1
	v_mov_b32_dpp v19, v22 quad_perm:[1,0,3,2] row_mask:0xf bank_mask:0xf
	s_waitcnt lgkmcnt(0)
	v_add_f32_e32 v19, v22, v19
	s_nop 1
	v_mov_b32_dpp v22, v19 quad_perm:[2,3,0,1] row_mask:0xf bank_mask:0xf
	s_waitcnt lgkmcnt(0)
	v_add_f32_e32 v19, v19, v22
	s_nop 1
	v_mov_b32_dpp v22, v19 row_half_mirror row_mask:0xf bank_mask:0xf
	s_waitcnt lgkmcnt(0)
	v_add_f32_e32 v19, v19, v22
	s_nop 1
	v_mov_b32_dpp v22, v19 row_mirror row_mask:0xf bank_mask:0xf
	s_waitcnt lgkmcnt(0)
	v_add_f32_e32 v19, v19, v22
	v_mov_b32_e32 v22, v19
	s_nop 1
	v_permlane16_swap_b32_e32 v19, v22
	s_waitcnt lgkmcnt(0)
	v_add_f32_e32 v19, v19, v22
	v_fmamk_f32 v19, v19, 0x3c000000, v179
	v_cmp_gt_f32_e32 vcc, s4, v19
	v_mul_f32_e32 v22, 0x4f800000, v19
	s_nop 0
	v_cndmask_b32_e32 v19, v19, v22, vcc
	v_sqrt_f32_e32 v22, v19
	s_nop 0
	v_add_u32_e32 v23, -1, v22
	v_fma_f32 v24, -v23, v22, v19
	v_cmp_ge_f32_e64 s[0:1], 0, v24
	v_add_u32_e32 v24, 1, v22
	s_nop 0
	v_cndmask_b32_e64 v23, v22, v23, s[0:1]
	v_fma_f32 v22, -v24, v22, v19
	v_cmp_lt_f32_e64 s[0:1], 0, v22
	s_nop 1
	v_cndmask_b32_e64 v22, v23, v24, s[0:1]
	v_mul_f32_e32 v23, 0x37800000, v22
	v_cndmask_b32_e32 v22, v22, v23, vcc
	v_cmp_class_f32_e32 vcc, v19, v180
	s_nop 1
	v_cndmask_b32_e32 v19, v22, v19, vcc
	v_div_scale_f32 v22, s[0:1], v19, v19, 1.0
	v_rcp_f32_e32 v23, v22
	s_nop 0
	v_fma_f32 v24, -v22, v23, 1.0
	v_fmac_f32_e32 v23, v24, v23
	v_div_scale_f32 v24, vcc, 1.0, v19, 1.0
	v_mul_f32_e32 v25, v24, v23
	v_fma_f32 v26, -v22, v25, v24
	v_fmac_f32_e32 v25, v26, v23
	v_fma_f32 v22, -v22, v25, v24
	v_div_fmas_f32 v22, v22, v23, v25
	v_div_fixup_f32 v19, v22, v19, 1.0
	v_mul_f32_e32 v20, v20, v19
	v_mul_f32_e32 v20, v34, v20
	v_bfe_u32 v22, v20, 16, 1
	v_add3_u32 v20, v20, v22, s70
	global_store_short_d16_hi v[16:17], v20, off
	v_mul_f32_e32 v20, v21, v19
	v_mul_f32_e32 v20, v35, v20
	v_bfe_u32 v21, v20, 16, 1
	v_mul_f32_e32 v9, v9, v19
	v_add3_u32 v20, v20, v21, s70
	v_mul_f32_e32 v9, v36, v9
	global_store_short_d16_hi v[16:17], v20, off offset:64
	v_bfe_u32 v20, v9, 16, 1
	v_add3_u32 v9, v9, v20, s70
	global_store_short_d16_hi v[16:17], v9, off offset:128
	v_mul_f32_e32 v9, v18, v19
	v_mul_f32_e32 v9, v37, v9
	v_bfe_u32 v18, v9, 16, 1
	v_add3_u32 v9, v9, v18, s70
	global_store_short_d16_hi v[16:17], v9, off offset:192
	v_add_u32_e32 v9, v14, v8
	v_lshl_add_u32 v9, v9, 7, v138
	v_lshl_add_u32 v9, v9, 2, 0
	ds_read2_b32 v[16:17], v9 offset1:32
	v_lshlrev_b64 v[14:15], 12, v[14:15]
	v_lshl_add_u64 v[14:15], v[4:5], 0, v[14:15]
	s_waitcnt lgkmcnt(0)
	v_fma_f32 v18, -v160, v16, v70
	v_fma_f32 v19, -v160, v17, v54
	ds_read2_b32 v[16:17], v9 offset0:64 offset1:96
	v_mul_f32_e32 v20, v19, v19
	v_fmac_f32_e32 v20, v18, v18
	s_waitcnt lgkmcnt(0)
	v_fma_f32 v9, -v160, v16, v44
	v_fmac_f32_e32 v20, v9, v9
	v_fma_f32 v16, -v160, v17, v45
	v_fmac_f32_e32 v20, v16, v16
	s_nop 1
	v_mov_b32_dpp v17, v20 quad_perm:[1,0,3,2] row_mask:0xf bank_mask:0xf
	s_waitcnt lgkmcnt(0)
	v_add_f32_e32 v17, v20, v17
	s_nop 1
	v_mov_b32_dpp v20, v17 quad_perm:[2,3,0,1] row_mask:0xf bank_mask:0xf
	s_waitcnt lgkmcnt(0)
; __device__ __forceinline__ unsigned f2bf(float f) { unsigned u = __builtin_bit_cast(unsigned, f); return (u + 0x7fffu + ((u >> 16) & 1u)) >> 16; }
; __device__ __forceinline__ int crow(int r, int hi) { return (r & 3) + 8 * (r >> 2) + 4 * hi; }
; __device__ __forceinline__ void attn_unit(const bf16* __restrict__ Qb, const bf16* __restrict__ Kh, const bf16* __restrict__ Vh, int klat0, int nlt, int kctx0, int NT,
;                                           float lam, float post, const float* __restrict__ subw, bf16* __restrict__ Ob, char* lds) {
;     ...
;     for (int r = 0; r < 16; ++r) { const int orow = crow(r, hi_e); float v[4]; float ss = 0.f;
; #pragma unroll
;       for (int d0 = 0; d0 < 4; ++d0) { v[d0] = o[d0][r] - lam * X[(wq_e * 32 + orow) * 128 + d0 * 32 + r32_e]; ss += v[d0] * v[d0]; }
;       ss += __shfl_xor(ss, 1); ss += __shfl_xor(ss, 2); ss += __shfl_xor(ss, 4); ss += __shfl_xor(ss, 8); ss += __shfl_xor(ss, 16);
;       const float rs = 1.0f / sqrtf(ss * (1.0f / 128.0f) + LN_EPS);
; #pragma unroll
;       for (int d0 = 0; d0 < 4; ++d0) Ow[(long)orow * DM + d0 * 32 + r32_e] = (bf16)f2bf(v[d0] * rs * sw[d0]); }
	v_add_f32_e32 v17, v17, v20
	s_nop 1
	v_mov_b32_dpp v20, v17 row_half_mirror row_mask:0xf bank_mask:0xf
	s_waitcnt lgkmcnt(0)
	v_add_f32_e32 v17, v17, v20
	s_nop 1
	v_mov_b32_dpp v20, v17 row_mirror row_mask:0xf bank_mask:0xf
	s_waitcnt lgkmcnt(0)
	v_add_f32_e32 v17, v17, v20
	v_mov_b32_e32 v20, v17
	s_nop 1
	v_permlane16_swap_b32_e32 v17, v20
	s_waitcnt lgkmcnt(0)
	v_add_f32_e32 v17, v17, v20
	v_fmamk_f32 v17, v17, 0x3c000000, v179
	v_cmp_gt_f32_e32 vcc, s4, v17
	v_mul_f32_e32 v20, 0x4f800000, v17
	s_nop 0
	v_cndmask_b32_e32 v17, v17, v20, vcc
	v_sqrt_f32_e32 v20, v17
	s_nop 0
	v_add_u32_e32 v21, -1, v20
	v_fma_f32 v22, -v21, v20, v17
	v_cmp_ge_f32_e64 s[0:1], 0, v22
	v_add_u32_e32 v22, 1, v20
	s_nop 0
	v_cndmask_b32_e64 v21, v20, v21, s[0:1]
	v_fma_f32 v20, -v22, v20, v17
	v_cmp_lt_f32_e64 s[0:1], 0, v20
	s_nop 1
	v_cndmask_b32_e64 v20, v21, v22, s[0:1]
	v_mul_f32_e32 v21, 0x37800000, v20
	v_cndmask_b32_e32 v20, v20, v21, vcc
	v_cmp_class_f32_e32 vcc, v17, v180
	s_nop 1
	v_cndmask_b32_e32 v17, v20, v17, vcc
	v_div_scale_f32 v20, s[0:1], v17, v17, 1.0
	v_rcp_f32_e32 v21, v20
	s_nop 0
	v_fma_f32 v22, -v20, v21, 1.0
	v_fmac_f32_e32 v21, v22, v21
	v_div_scale_f32 v22, vcc, 1.0, v17, 1.0
	v_mul_f32_e32 v23, v22, v21
	v_fma_f32 v24, -v20, v23, v22
	v_fmac_f32_e32 v23, v24, v21
	v_fma_f32 v20, -v20, v23, v22
	v_div_fmas_f32 v20, v20, v21, v23
	v_div_fixup_f32 v17, v20, v17, 1.0
	v_mul_f32_e32 v18, v18, v17
	v_mul_f32_e32 v18, v34, v18
	v_bfe_u32 v20, v18, 16, 1
	v_add3_u32 v18, v18, v20, s70
	global_store_short_d16_hi v[14:15], v18, off
	v_mul_f32_e32 v18, v19, v17
	v_mul_f32_e32 v18, v35, v18
	v_bfe_u32 v19, v18, 16, 1
	v_mul_f32_e32 v9, v9, v17
	v_add3_u32 v18, v18, v19, s70
	v_mul_f32_e32 v9, v36, v9
	global_store_short_d16_hi v[14:15], v18, off offset:64
	v_bfe_u32 v18, v9, 16, 1
	v_add3_u32 v9, v9, v18, s70
	global_store_short_d16_hi v[14:15], v9, off offset:128
	v_mul_f32_e32 v9, v16, v17
	v_mul_f32_e32 v9, v37, v9
	v_bfe_u32 v16, v9, 16, 1
	v_add3_u32 v9, v9, v16, s70
	global_store_short_d16_hi v[14:15], v9, off offset:192
	v_add_u32_e32 v9, v12, v8
	v_lshl_add_u32 v9, v9, 7, v138
	v_lshl_add_u32 v9, v9, 2, 0
	ds_read2_b32 v[14:15], v9 offset1:32
	v_lshlrev_b64 v[12:13], 12, v[12:13]
	v_lshl_add_u64 v[12:13], v[4:5], 0, v[12:13]
	s_waitcnt lgkmcnt(0)
	v_fma_f32 v16, -v160, v14, v69
	v_fma_f32 v17, -v160, v15, v53
	ds_read2_b32 v[14:15], v9 offset0:64 offset1:96
	v_mul_f32_e32 v18, v17, v17
	v_fmac_f32_e32 v18, v16, v16
	s_waitcnt lgkmcnt(0)
	v_fma_f32 v9, -v160, v14, v42
	v_fmac_f32_e32 v18, v9, v9
	v_fma_f32 v14, -v160, v15, v43
	v_fmac_f32_e32 v18, v14, v14
	s_nop 1
	v_mov_b32_dpp v15, v18 quad_perm:[1,0,3,2] row_mask:0xf bank_mask:0xf
	s_waitcnt lgkmcnt(0)
	v_add_f32_e32 v15, v18, v15
	s_nop 1
	v_mov_b32_dpp v18, v15 quad_perm:[2,3,0,1] row_mask:0xf bank_mask:0xf
	s_waitcnt lgkmcnt(0)
	v_add_f32_e32 v15, v15, v18
	s_nop 1
	v_mov_b32_dpp v18, v15 row_half_mirror row_mask:0xf bank_mask:0xf
	s_waitcnt lgkmcnt(0)
	v_add_f32_e32 v15, v15, v18
	s_nop 1
	v_mov_b32_dpp v18, v15 row_mirror row_mask:0xf bank_mask:0xf
	s_waitcnt lgkmcnt(0)
	v_add_f32_e32 v15, v15, v18
	v_mov_b32_e32 v18, v15
	s_nop 1
	v_permlane16_swap_b32_e32 v15, v18
	s_waitcnt lgkmcnt(0)
	v_add_f32_e32 v15, v15, v18
	v_fmamk_f32 v15, v15, 0x3c000000, v179
	v_cmp_gt_f32_e32 vcc, s4, v15
	v_mul_f32_e32 v18, 0x4f800000, v15
	s_nop 0
	v_cndmask_b32_e32 v15, v15, v18, vcc
	v_sqrt_f32_e32 v18, v15
	s_nop 0
	v_add_u32_e32 v19, -1, v18
	v_fma_f32 v20, -v19, v18, v15
	v_cmp_ge_f32_e64 s[0:1], 0, v20
	v_add_u32_e32 v20, 1, v18
	s_nop 0
	v_cndmask_b32_e64 v19, v18, v19, s[0:1]
	v_fma_f32 v18, -v20, v18, v15
	v_cmp_lt_f32_e64 s[0:1], 0, v18
	s_nop 1
	v_cndmask_b32_e64 v18, v19, v20, s[0:1]
	v_mul_f32_e32 v19, 0x37800000, v18
	v_cndmask_b32_e32 v18, v18, v19, vcc
	v_cmp_class_f32_e32 vcc, v15, v180
	s_nop 1
	v_cndmask_b32_e32 v15, v18, v15, vcc
	v_div_scale_f32 v18, s[0:1], v15, v15, 1.0
	v_rcp_f32_e32 v19, v18
	s_nop 0
	v_fma_f32 v20, -v18, v19, 1.0
	v_fmac_f32_e32 v19, v20, v19
	v_div_scale_f32 v20, vcc, 1.0, v15, 1.0
	v_mul_f32_e32 v21, v20, v19
	v_fma_f32 v22, -v18, v21, v20
	v_fmac_f32_e32 v21, v22, v19
	v_fma_f32 v18, -v18, v21, v20
	v_div_fmas_f32 v18, v18, v19, v21
	v_div_fixup_f32 v15, v18, v15, 1.0
	v_mul_f32_e32 v16, v16, v15
	v_mul_f32_e32 v16, v34, v16
	v_bfe_u32 v18, v16, 16, 1
	v_add3_u32 v16, v16, v18, s70
	global_store_short_d16_hi v[12:13], v16, off
	v_mul_f32_e32 v16, v17, v15
	v_mul_f32_e32 v16, v35, v16
	v_bfe_u32 v17, v16, 16, 1
	v_mul_f32_e32 v9, v9, v15
	v_add3_u32 v16, v16, v17, s70
	v_mul_f32_e32 v9, v36, v9
	global_store_short_d16_hi v[12:13], v16, off offset:64
	v_bfe_u32 v16, v9, 16, 1
	v_add3_u32 v9, v9, v16, s70
	global_store_short_d16_hi v[12:13], v9, off offset:128
	v_mul_f32_e32 v9, v14, v15
	v_mul_f32_e32 v9, v37, v9
	v_bfe_u32 v14, v9, 16, 1
	v_add3_u32 v9, v9, v14, s70
	global_store_short_d16_hi v[12:13], v9, off offset:192
	v_add_u32_e32 v9, v10, v8
	v_lshl_add_u32 v9, v9, 7, v138
	v_lshl_add_u32 v9, v9, 2, 0
	ds_read2_b32 v[12:13], v9 offset1:32
	v_lshlrev_b64 v[10:11], 12, v[10:11]
	v_lshl_add_u64 v[10:11], v[4:5], 0, v[10:11]
	s_waitcnt lgkmcnt(0)
	v_fma_f32 v14, -v160, v12, v68
	v_fma_f32 v15, -v160, v13, v52
	ds_read2_b32 v[12:13], v9 offset0:64 offset1:96
	v_mul_f32_e32 v16, v15, v15
	v_fmac_f32_e32 v16, v14, v14
	s_waitcnt lgkmcnt(0)
	v_fma_f32 v9, -v160, v12, v40
	v_fmac_f32_e32 v16, v9, v9
	v_fma_f32 v12, -v160, v13, v41
	v_fmac_f32_e32 v16, v12, v12
	s_nop 1
	v_mov_b32_dpp v13, v16 quad_perm:[1,0,3,2] row_mask:0xf bank_mask:0xf
	s_waitcnt lgkmcnt(0)
	v_add_f32_e32 v13, v16, v13
	s_nop 1
	v_mov_b32_dpp v16, v13 quad_perm:[2,3,0,1] row_mask:0xf bank_mask:0xf
	s_waitcnt lgkmcnt(0)
; __device__ __forceinline__ unsigned f2bf(float f) { unsigned u = __builtin_bit_cast(unsigned, f); return (u + 0x7fffu + ((u >> 16) & 1u)) >> 16; }
; __device__ __forceinline__ int crow(int r, int hi) { return (r & 3) + 8 * (r >> 2) + 4 * hi; }
; __device__ __forceinline__ void attn_unit(const bf16* __restrict__ Qb, const bf16* __restrict__ Kh, const bf16* __restrict__ Vh, int klat0, int nlt, int kctx0, int NT,
;                                           float lam, float post, const float* __restrict__ subw, bf16* __restrict__ Ob, char* lds) {
;     ...
;     for (int r = 0; r < 16; ++r) { const int orow = crow(r, hi_e); float v[4]; float ss = 0.f;
; #pragma unroll
;       for (int d0 = 0; d0 < 4; ++d0) { v[d0] = o[d0][r] - lam * X[(wq_e * 32 + orow) * 128 + d0 * 32 + r32_e]; ss += v[d0] * v[d0]; }
;       ss += __shfl_xor(ss, 1); ss += __shfl_xor(ss, 2); ss += __shfl_xor(ss, 4); ss += __shfl_xor(ss, 8); ss += __shfl_xor(ss, 16);
;       const float rs = 1.0f / sqrtf(ss * (1.0f / 128.0f) + LN_EPS);
; #pragma unroll
;       for (int d0 = 0; d0 < 4; ++d0) Ow[(long)orow * DM + d0 * 32 + r32_e] = (bf16)f2bf(v[d0] * rs * sw[d0]); }
	v_add_f32_e32 v13, v13, v16
	s_nop 1
	v_mov_b32_dpp v16, v13 row_half_mirror row_mask:0xf bank_mask:0xf
	s_waitcnt lgkmcnt(0)
	v_add_f32_e32 v13, v13, v16
	s_nop 1
	v_mov_b32_dpp v16, v13 row_mirror row_mask:0xf bank_mask:0xf
	s_waitcnt lgkmcnt(0)
	v_add_f32_e32 v13, v13, v16
	v_mov_b32_e32 v16, v13
	s_nop 1
	v_permlane16_swap_b32_e32 v13, v16
	s_waitcnt lgkmcnt(0)
	v_add_f32_e32 v13, v13, v16
	v_fmamk_f32 v13, v13, 0x3c000000, v179
	v_cmp_gt_f32_e32 vcc, s4, v13
	v_mul_f32_e32 v16, 0x4f800000, v13
	s_nop 0
	v_cndmask_b32_e32 v13, v13, v16, vcc
	v_sqrt_f32_e32 v16, v13
	s_nop 0
	v_add_u32_e32 v17, -1, v16
	v_fma_f32 v18, -v17, v16, v13
	v_cmp_ge_f32_e64 s[0:1], 0, v18
	v_add_u32_e32 v18, 1, v16
	s_nop 0
	v_cndmask_b32_e64 v17, v16, v17, s[0:1]
	v_fma_f32 v16, -v18, v16, v13
	v_cmp_lt_f32_e64 s[0:1], 0, v16
	s_nop 1
	v_cndmask_b32_e64 v16, v17, v18, s[0:1]
	v_mul_f32_e32 v17, 0x37800000, v16
	v_cndmask_b32_e32 v16, v16, v17, vcc
	v_cmp_class_f32_e32 vcc, v13, v180
	s_nop 1
	v_cndmask_b32_e32 v13, v16, v13, vcc
	v_div_scale_f32 v16, s[0:1], v13, v13, 1.0
	v_rcp_f32_e32 v17, v16
	s_nop 0
	v_fma_f32 v18, -v16, v17, 1.0
	v_fmac_f32_e32 v17, v18, v17
	v_div_scale_f32 v18, vcc, 1.0, v13, 1.0
	v_mul_f32_e32 v19, v18, v17
	v_fma_f32 v20, -v16, v19, v18
	v_fmac_f32_e32 v19, v20, v17
	v_fma_f32 v16, -v16, v19, v18
	v_div_fmas_f32 v16, v16, v17, v19
	v_div_fixup_f32 v13, v16, v13, 1.0
	v_mul_f32_e32 v14, v14, v13
	v_mul_f32_e32 v14, v34, v14
	v_bfe_u32 v16, v14, 16, 1
	v_add3_u32 v14, v14, v16, s70
	global_store_short_d16_hi v[10:11], v14, off
	v_mul_f32_e32 v14, v15, v13
	v_mul_f32_e32 v14, v35, v14
	v_bfe_u32 v15, v14, 16, 1
	v_mul_f32_e32 v9, v9, v13
	v_add3_u32 v14, v14, v15, s70
	v_mul_f32_e32 v9, v36, v9
	global_store_short_d16_hi v[10:11], v14, off offset:64
	v_bfe_u32 v14, v9, 16, 1
	v_add3_u32 v9, v9, v14, s70
	global_store_short_d16_hi v[10:11], v9, off offset:128
	v_mul_f32_e32 v9, v12, v13
	v_mul_f32_e32 v9, v37, v9
	v_bfe_u32 v12, v9, 16, 1
	v_add3_u32 v9, v9, v12, s70
	global_store_short_d16_hi v[10:11], v9, off offset:192
	v_add_u32_e32 v9, v6, v8
	v_lshl_add_u32 v9, v9, 7, v138
	v_lshl_add_u32 v9, v9, 2, 0
	ds_read2_b32 v[10:11], v9 offset1:32
	v_lshlrev_b64 v[6:7], 12, v[6:7]
	v_lshl_add_u64 v[6:7], v[4:5], 0, v[6:7]
	s_waitcnt lgkmcnt(0)
	v_fma_f32 v12, -v160, v10, v67
	v_fma_f32 v13, -v160, v11, v51
	ds_read2_b32 v[10:11], v9 offset0:64 offset1:96
	v_mul_f32_e32 v14, v13, v13
	v_fmac_f32_e32 v14, v12, v12
	s_waitcnt lgkmcnt(0)
	v_fma_f32 v9, -v160, v10, v38
	v_fmac_f32_e32 v14, v9, v9
	v_fma_f32 v10, -v160, v11, v39
	v_fmac_f32_e32 v14, v10, v10
	s_nop 1
	v_mov_b32_dpp v11, v14 quad_perm:[1,0,3,2] row_mask:0xf bank_mask:0xf
	s_waitcnt lgkmcnt(0)
	v_add_f32_e32 v11, v14, v11
	s_nop 1
	v_mov_b32_dpp v14, v11 quad_perm:[2,3,0,1] row_mask:0xf bank_mask:0xf
	s_waitcnt lgkmcnt(0)
	v_add_f32_e32 v11, v11, v14
	s_nop 1
	v_mov_b32_dpp v14, v11 row_half_mirror row_mask:0xf bank_mask:0xf
	s_waitcnt lgkmcnt(0)
	v_add_f32_e32 v11, v11, v14
	s_nop 1
	v_mov_b32_dpp v14, v11 row_mirror row_mask:0xf bank_mask:0xf
	s_waitcnt lgkmcnt(0)
	v_add_f32_e32 v11, v11, v14
	v_mov_b32_e32 v14, v11
	s_nop 1
	v_permlane16_swap_b32_e32 v11, v14
	s_waitcnt lgkmcnt(0)
; __device__ __forceinline__ unsigned f2bf(float f) { unsigned u = __builtin_bit_cast(unsigned, f); return (u + 0x7fffu + ((u >> 16) & 1u)) >> 16; }
; __device__ __forceinline__ int crow(int r, int hi) { return (r & 3) + 8 * (r >> 2) + 4 * hi; }
; __device__ __forceinline__ void attn_unit(const bf16* __restrict__ Qb, const bf16* __restrict__ Kh, const bf16* __restrict__ Vh, int klat0, int nlt, int kctx0, int NT,
;                                           float lam, float post, const float* __restrict__ subw, bf16* __restrict__ Ob, char* lds) {
;     ...
;     for (int r = 0; r < 16; ++r) { const int orow = crow(r, hi_e); float v[4]; float ss = 0.f;
; #pragma unroll
;       for (int d0 = 0; d0 < 4; ++d0) { v[d0] = o[d0][r] - lam * X[(wq_e * 32 + orow) * 128 + d0 * 32 + r32_e]; ss += v[d0] * v[d0]; }
;       ss += __shfl_xor(ss, 1); ss += __shfl_xor(ss, 2); ss += __shfl_xor(ss, 4); ss += __shfl_xor(ss, 8); ss += __shfl_xor(ss, 16);
;       const float rs = 1.0f / sqrtf(ss * (1.0f / 128.0f) + LN_EPS);
; #pragma unroll
;       for (int d0 = 0; d0 < 4; ++d0) Ow[(long)orow * DM + d0 * 32 + r32_e] = (bf16)f2bf(v[d0] * rs * sw[d0]); }
;   }
	v_add_f32_e32 v11, v11, v14
	v_fmamk_f32 v11, v11, 0x3c000000, v179
	v_cmp_gt_f32_e32 vcc, s4, v11
	v_mul_f32_e32 v14, 0x4f800000, v11
	s_nop 0
	v_cndmask_b32_e32 v11, v11, v14, vcc
	v_sqrt_f32_e32 v14, v11
	s_nop 0
	v_add_u32_e32 v15, -1, v14
	v_fma_f32 v16, -v15, v14, v11
	v_cmp_ge_f32_e64 s[0:1], 0, v16
	v_add_u32_e32 v16, 1, v14
	s_nop 0
	v_cndmask_b32_e64 v15, v14, v15, s[0:1]
	v_fma_f32 v14, -v16, v14, v11
	v_cmp_lt_f32_e64 s[0:1], 0, v14
	s_nop 1
	v_cndmask_b32_e64 v14, v15, v16, s[0:1]
	v_mul_f32_e32 v15, 0x37800000, v14
	v_cndmask_b32_e32 v14, v14, v15, vcc
	v_cmp_class_f32_e32 vcc, v11, v180
	s_nop 1
	v_cndmask_b32_e32 v11, v14, v11, vcc
	v_div_scale_f32 v14, s[0:1], v11, v11, 1.0
	v_rcp_f32_e32 v15, v14
	s_nop 0
	v_fma_f32 v16, -v14, v15, 1.0
	v_fmac_f32_e32 v15, v16, v15
	v_div_scale_f32 v16, vcc, 1.0, v11, 1.0
	v_mul_f32_e32 v17, v16, v15
	v_fma_f32 v18, -v14, v17, v16
	v_fmac_f32_e32 v17, v18, v15
	v_fma_f32 v14, -v14, v17, v16
	v_div_fmas_f32 v14, v14, v15, v17
	v_div_fixup_f32 v11, v14, v11, 1.0
	v_mul_f32_e32 v12, v12, v11
	v_mul_f32_e32 v12, v34, v12
	v_bfe_u32 v14, v12, 16, 1
	v_add3_u32 v12, v12, v14, s70
	global_store_short_d16_hi v[6:7], v12, off
	v_mul_f32_e32 v12, v13, v11
	v_mul_f32_e32 v12, v35, v12
	v_bfe_u32 v13, v12, 16, 1
	v_mul_f32_e32 v9, v9, v11
	v_add3_u32 v12, v12, v13, s70
	v_mul_f32_e32 v9, v36, v9
	global_store_short_d16_hi v[6:7], v12, off offset:64
	v_bfe_u32 v12, v9, 16, 1
	v_add3_u32 v9, v9, v12, s70
	global_store_short_d16_hi v[6:7], v9, off offset:128
	v_mul_f32_e32 v9, v10, v11
	v_mul_f32_e32 v9, v37, v9
	v_bfe_u32 v10, v9, 16, 1
	v_add3_u32 v9, v9, v10, s70
	global_store_short_d16_hi v[6:7], v9, off offset:192
	v_add_u32_e32 v6, v2, v8
	v_lshl_add_u32 v6, v6, 7, v138
	v_lshl_add_u32 v8, v6, 2, 0
	ds_read2_b32 v[6:7], v8 offset1:32
	v_lshlrev_b64 v[2:3], 12, v[2:3]
	v_lshl_add_u64 v[2:3], v[4:5], 0, v[2:3]
	s_waitcnt lgkmcnt(0)
	v_fma_f32 v9, -v160, v6, v66
	v_fma_f32 v10, -v160, v7, v50
	ds_read2_b32 v[6:7], v8 offset0:64 offset1:96
	v_mul_f32_e32 v11, v10, v10
	v_fmac_f32_e32 v11, v9, v9
	s_waitcnt lgkmcnt(0)
	v_fma_f32 v6, -v160, v6, v32
	v_fmac_f32_e32 v11, v6, v6
	v_fma_f32 v7, -v160, v7, v33
	v_fmac_f32_e32 v11, v7, v7
	s_nop 1
	v_mov_b32_dpp v8, v11 quad_perm:[1,0,3,2] row_mask:0xf bank_mask:0xf
	s_waitcnt lgkmcnt(0)
	v_add_f32_e32 v8, v11, v8
	s_nop 1
	v_mov_b32_dpp v11, v8 quad_perm:[2,3,0,1] row_mask:0xf bank_mask:0xf
	s_waitcnt lgkmcnt(0)
	v_add_f32_e32 v8, v8, v11
	s_nop 1
	v_mov_b32_dpp v11, v8 row_half_mirror row_mask:0xf bank_mask:0xf
	s_waitcnt lgkmcnt(0)
	v_add_f32_e32 v8, v8, v11
	s_nop 1
	v_mov_b32_dpp v11, v8 row_mirror row_mask:0xf bank_mask:0xf
	s_waitcnt lgkmcnt(0)
	v_add_f32_e32 v8, v8, v11
	v_mov_b32_e32 v11, v8
	s_nop 1
	v_permlane16_swap_b32_e32 v8, v11
	s_waitcnt lgkmcnt(0)
	v_add_f32_e32 v8, v8, v11
	v_fmamk_f32 v8, v8, 0x3c000000, v179
	v_cmp_gt_f32_e32 vcc, s4, v8
	v_mul_f32_e32 v11, 0x4f800000, v8
	s_nop 0
	v_cndmask_b32_e32 v8, v8, v11, vcc
	v_sqrt_f32_e32 v11, v8
	s_nop 0
	v_add_u32_e32 v12, -1, v11
	v_fma_f32 v13, -v12, v11, v8
	v_cmp_ge_f32_e64 s[0:1], 0, v13
	v_add_u32_e32 v13, 1, v11
	s_nop 0
	v_cndmask_b32_e64 v12, v11, v12, s[0:1]
	v_fma_f32 v11, -v13, v11, v8
	v_cmp_lt_f32_e64 s[0:1], 0, v11
	s_nop 1
	v_cndmask_b32_e64 v11, v12, v13, s[0:1]
	v_mul_f32_e32 v12, 0x37800000, v11
	v_cndmask_b32_e32 v11, v11, v12, vcc
	v_cmp_class_f32_e32 vcc, v8, v180
	s_nop 1
	v_cndmask_b32_e32 v8, v11, v8, vcc
	v_div_scale_f32 v11, s[0:1], v8, v8, 1.0
	v_rcp_f32_e32 v12, v11
	s_nop 0
	v_fma_f32 v13, -v11, v12, 1.0
	v_fmac_f32_e32 v12, v13, v12
	v_div_scale_f32 v13, vcc, 1.0, v8, 1.0
	v_mul_f32_e32 v14, v13, v12
	v_fma_f32 v15, -v11, v14, v13
	v_fmac_f32_e32 v14, v15, v12
	v_fma_f32 v11, -v11, v14, v13
	v_div_fmas_f32 v11, v11, v12, v14
	v_div_fixup_f32 v8, v11, v8, 1.0
	v_mul_f32_e32 v4, v9, v8
	v_mul_f32_e32 v4, v34, v4
	v_bfe_u32 v5, v4, 16, 1
	v_add3_u32 v4, v4, v5, s70
	global_store_short_d16_hi v[2:3], v4, off
	v_mul_f32_e32 v4, v10, v8
	v_mul_f32_e32 v4, v35, v4
	v_bfe_u32 v5, v4, 16, 1
	v_add3_u32 v4, v4, v5, s70
	global_store_short_d16_hi v[2:3], v4, off offset:64
	v_mul_f32_e32 v4, v6, v8
	v_mul_f32_e32 v4, v36, v4
	v_bfe_u32 v5, v4, 16, 1
	v_add3_u32 v4, v4, v5, s70
	global_store_short_d16_hi v[2:3], v4, off offset:128
	v_mul_f32_e32 v4, v7, v8
	v_mul_f32_e32 v4, v37, v4
	v_bfe_u32 v5, v4, 16, 1
	v_add3_u32 v4, v4, v5, s70
	global_store_short_d16_hi v[2:3], v4, off offset:192
	s_branch .LBB0_714
